# grid-barrier poll-latency trim: s_sleep removed from the xcd-barrier spin loops, on static-prio base
# baseline (speedup 1.0000x reference)
; #define KARG(name) KP name = (KP)__builtin_amdgcn_kernarg_segment_ptr(); asm volatile("" : "+s"(name))
; __global__ void __launch_bounds__(NTHREADS, 2) fwd_megakernel(Params P) {
;     ...
;     { KARG(kpc); if (kpc->ws == nullptr) grid.sync(); }
.LBB0_14:
	global_load_dword v2, v0, s[6:7] offset:32 sc1
	s_waitcnt vmcnt(0)
	v_and_b32_e32 v2, 0xffff0000, v2
	v_cmp_ne_u32_e32 vcc, v2, v1
	s_or_b64 s[8:9], vcc, s[8:9]
	s_andn2_b64 exec, exec, s[8:9]
	s_cbranch_execnz .LBB0_14

; __device__ __forceinline__ unsigned xb_ld(unsigned* p)              { return __hip_atomic_load(p, __ATOMIC_RELAXED, __HIP_MEMORY_SCOPE_AGENT); }
; __device__ __forceinline__ void xcd_barrier_complete(unsigned* bar, unsigned x, unsigned& nloc, unsigned& nx) {
;     ...
;     for (;;) {
;         sum = 0u; cnt = 0u; mine = 0u;
; #pragma unroll
;         for (unsigned j = 0; j < 16; ++j) { const unsigned c = xb_ld(&bar[XB_XCNT(j)]); sum += c; cnt += (c > 0u) ? 1u : 0u; mine = (j == x) ? c : mine; }
;         if (sum == G) break;
;         __builtin_amdgcn_s_sleep(1);
;         if ((++sp & 255u) == 0u) { if (xb_ld(&bar[XB_TMO])) break; if (sp > XB_SPIN_CAP) { atomicAdd(&bar[XB_TMO], 1u); break; } }
;     }
.LBB0_51:
	global_load_dword v15, v16, s[8:9] sc1
	global_load_dword v0, v16, s[10:11] sc1
	global_load_dword v1, v16, s[12:13] sc1
	global_load_dword v2, v16, s[16:17] sc1
	global_load_dword v3, v16, s[18:19] sc1
	global_load_dword v4, v16, s[28:29] sc1
	global_load_dword v5, v16, s[30:31] sc1
	global_load_dword v6, v16, s[34:35] sc1
	global_load_dword v7, v16, s[36:37] sc1
	global_load_dword v8, v16, s[38:39] sc1
	global_load_dword v9, v16, s[40:41] sc1
	global_load_dword v10, v16, s[42:43] sc1
	global_load_dword v11, v16, s[44:45] sc1
	global_load_dword v12, v16, s[46:47] sc1
	global_load_dword v13, v16, s[48:49] sc1
	global_load_dword v14, v16, s[50:51] sc1
	s_mov_b64 s[52:53], -1
	s_mov_b64 s[54:55], -1
	s_waitcnt vmcnt(14)
	v_add_u32_e32 v17, v0, v15
	s_waitcnt vmcnt(13)
	v_add_u32_e32 v17, v17, v1
	s_waitcnt vmcnt(12)
	v_add_u32_e32 v17, v17, v2
	s_waitcnt vmcnt(11)
	v_add_u32_e32 v17, v17, v3
	s_waitcnt vmcnt(10)
	v_add_u32_e32 v17, v17, v4
	s_waitcnt vmcnt(9)
	v_add_u32_e32 v17, v17, v5
	s_waitcnt vmcnt(8)
	v_add_u32_e32 v17, v17, v6
	s_waitcnt vmcnt(7)
	v_add_u32_e32 v17, v17, v7
	s_waitcnt vmcnt(6)
	v_add_u32_e32 v17, v17, v8
	s_waitcnt vmcnt(5)
	v_add_u32_e32 v17, v17, v9
	s_waitcnt vmcnt(4)
	v_add_u32_e32 v17, v17, v10
	s_waitcnt vmcnt(3)
	v_add_u32_e32 v17, v17, v11
	s_waitcnt vmcnt(2)
	v_add_u32_e32 v17, v17, v12
	s_waitcnt vmcnt(1)
	v_add_u32_e32 v17, v17, v13
	s_waitcnt vmcnt(0)
	v_add_u32_e32 v17, v17, v14
	v_cmp_eq_u32_e32 vcc, s27, v17
	s_cbranch_vccnz .LBB0_50
	s_and_b32 s52, s33, 0xff
	s_cmp_eq_u32 s52, 0
	s_mov_b64 s[52:53], -1
	s_mov_b64 s[56:57], -1
	s_cbranch_scc1 .LBB0_55
	s_and_b64 vcc, exec, s[56:57]
	s_cbranch_vccz .LBB0_50

; __device__ __forceinline__ unsigned xb_ld(unsigned* p)              { return __hip_atomic_load(p, __ATOMIC_RELAXED, __HIP_MEMORY_SCOPE_AGENT); }
; __device__ __forceinline__ unsigned xb_add(unsigned* p, unsigned v) { return __hip_atomic_fetch_add(p, v, __ATOMIC_RELAXED, __HIP_MEMORY_SCOPE_AGENT); }
; #define XB_SPIN(cond, bar) do { unsigned _sp = 0; while (cond) { __builtin_amdgcn_s_sleep(1); \
;     if ((++_sp & 255u) == 0u) { if (xb_ld(&(bar)[XB_TMO])) break; if (_sp > XB_SPIN_CAP) { atomicAdd(&(bar)[XB_TMO], 1u); break; } } } } while (0)
; __device__ __forceinline__ void xcd_barrier(const XcdBarrier& b) {
;     ...
;             else XB_SPIN(xb_ld(&bar[XB_TOPGEN]) == tg, bar);
;             __builtin_amdgcn_fence(__ATOMIC_ACQUIRE, "agent");
;             xb_add(&bar[XB_XGEN(b.x)], 1u);
;             asm volatile("s_waitcnt vmcnt(0)" ::: "memory");
;         } else {
;             XB_SPIN(xb_ld(&bar[XB_XGEN(b.x)]) == gen, bar);
.LBB0_69:
	s_and_b32 s33, s27, 0xff
	s_mov_b64 s[30:31], -1
	s_cmp_lg_u32 s33, 0
	s_mov_b64 s[36:37], -1
	s_cbranch_scc0 .LBB0_72
	s_and_b64 vcc, exec, s[36:37]
	s_cbranch_vccz .LBB0_68

; __device__ __forceinline__ unsigned xb_ld(unsigned* p)              { return __hip_atomic_load(p, __ATOMIC_RELAXED, __HIP_MEMORY_SCOPE_AGENT); }
; __device__ __forceinline__ unsigned xb_add(unsigned* p, unsigned v) { return __hip_atomic_fetch_add(p, v, __ATOMIC_RELAXED, __HIP_MEMORY_SCOPE_AGENT); }
; #define XB_SPIN(cond, bar) do { unsigned _sp = 0; while (cond) { __builtin_amdgcn_s_sleep(1); \
;     if ((++_sp & 255u) == 0u) { if (xb_ld(&(bar)[XB_TMO])) break; if (_sp > XB_SPIN_CAP) { atomicAdd(&(bar)[XB_TMO], 1u); break; } } } } while (0)
; __device__ __forceinline__ void xcd_barrier(const XcdBarrier& b) {
;     ...
;             else XB_SPIN(xb_ld(&bar[XB_TOPGEN]) == tg, bar);
;             __builtin_amdgcn_fence(__ATOMIC_ACQUIRE, "agent");
;             xb_add(&bar[XB_XGEN(b.x)], 1u);
;             asm volatile("s_waitcnt vmcnt(0)" ::: "memory");
;         } else {
;             XB_SPIN(xb_ld(&bar[XB_XGEN(b.x)]) == gen, bar);
.LBB0_86:
	s_and_b32 s30, s27, 0xff
	s_cmp_lg_u32 s30, 0
	s_mov_b64 s[34:35], -1
	s_cbranch_scc0 .LBB0_89
	s_mov_b64 s[36:37], -1
	s_and_b64 vcc, exec, s[34:35]
	s_cbranch_vccz .LBB0_85

; __device__ __forceinline__ unsigned xb_ld(unsigned* p)              { return __hip_atomic_load(p, __ATOMIC_RELAXED, __HIP_MEMORY_SCOPE_AGENT); }
; __device__ __forceinline__ void xcd_barrier_complete(unsigned* bar, unsigned x, unsigned& nloc, unsigned& nx) {
;     ...
;     for (;;) {
;         sum = 0u; cnt = 0u; mine = 0u;
; #pragma unroll
;         for (unsigned j = 0; j < 16; ++j) { const unsigned c = xb_ld(&bar[XB_XCNT(j)]); sum += c; cnt += (c > 0u) ? 1u : 0u; mine = (j == x) ? c : mine; }
;         if (sum == G) break;
;         __builtin_amdgcn_s_sleep(1);
;         if ((++sp & 255u) == 0u) { if (xb_ld(&bar[XB_TMO])) break; if (sp > XB_SPIN_CAP) { atomicAdd(&bar[XB_TMO], 1u); break; } }
;     }
.LBB0_178:
	global_load_dword v15, v16, s[8:9] sc1
	global_load_dword v0, v16, s[10:11] sc1
	global_load_dword v1, v16, s[16:17] sc1
	global_load_dword v2, v16, s[18:19] sc1
	global_load_dword v3, v16, s[30:31] sc1
	global_load_dword v4, v16, s[34:35] sc1
	global_load_dword v5, v16, s[36:37] sc1
	global_load_dword v6, v16, s[38:39] sc1
	global_load_dword v7, v16, s[40:41] sc1
	global_load_dword v8, v16, s[42:43] sc1
	global_load_dword v9, v16, s[44:45] sc1
	global_load_dword v10, v16, s[46:47] sc1
	global_load_dword v11, v16, s[48:49] sc1
	global_load_dword v12, v16, s[50:51] sc1
	global_load_dword v13, v16, s[52:53] sc1
	global_load_dword v14, v16, s[54:55] sc1
	s_mov_b64 s[56:57], -1
	s_mov_b64 s[58:59], -1
	s_waitcnt vmcnt(14)
	v_add_u32_e32 v17, v0, v15
	s_waitcnt vmcnt(13)
	v_add_u32_e32 v17, v17, v1
	s_waitcnt vmcnt(12)
	v_add_u32_e32 v17, v17, v2
	s_waitcnt vmcnt(11)
	v_add_u32_e32 v17, v17, v3
	s_waitcnt vmcnt(10)
	v_add_u32_e32 v17, v17, v4
	s_waitcnt vmcnt(9)
	v_add_u32_e32 v17, v17, v5
	s_waitcnt vmcnt(8)
	v_add_u32_e32 v17, v17, v6
	s_waitcnt vmcnt(7)
	v_add_u32_e32 v17, v17, v7
	s_waitcnt vmcnt(6)
	v_add_u32_e32 v17, v17, v8
	s_waitcnt vmcnt(5)
	v_add_u32_e32 v17, v17, v9
	s_waitcnt vmcnt(4)
	v_add_u32_e32 v17, v17, v10
	s_waitcnt vmcnt(3)
	v_add_u32_e32 v17, v17, v11
	s_waitcnt vmcnt(2)
	v_add_u32_e32 v17, v17, v12
	s_waitcnt vmcnt(1)
	v_add_u32_e32 v17, v17, v13
	s_waitcnt vmcnt(0)
	v_add_u32_e32 v17, v17, v14
	v_cmp_eq_u32_e32 vcc, s62, v17
	s_cbranch_vccnz .LBB0_177
	s_and_b32 s56, s33, 0xff
	s_cmp_eq_u32 s56, 0
	s_mov_b64 s[56:57], -1
	s_mov_b64 s[60:61], -1
	s_cbranch_scc1 .LBB0_182
	s_and_b64 vcc, exec, s[60:61]
	s_cbranch_vccz .LBB0_177

; __device__ __forceinline__ unsigned xb_ld(unsigned* p)              { return __hip_atomic_load(p, __ATOMIC_RELAXED, __HIP_MEMORY_SCOPE_AGENT); }
; __device__ __forceinline__ unsigned xb_add(unsigned* p, unsigned v) { return __hip_atomic_fetch_add(p, v, __ATOMIC_RELAXED, __HIP_MEMORY_SCOPE_AGENT); }
; #define XB_SPIN(cond, bar) do { unsigned _sp = 0; while (cond) { __builtin_amdgcn_s_sleep(1); \
;     if ((++_sp & 255u) == 0u) { if (xb_ld(&(bar)[XB_TMO])) break; if (_sp > XB_SPIN_CAP) { atomicAdd(&(bar)[XB_TMO], 1u); break; } } } } while (0)
; __device__ __forceinline__ void xcd_barrier(const XcdBarrier& b) {
;     ...
;             else XB_SPIN(xb_ld(&bar[XB_TOPGEN]) == tg, bar);
;             __builtin_amdgcn_fence(__ATOMIC_ACQUIRE, "agent");
;             xb_add(&bar[XB_XGEN(b.x)], 1u);
;             asm volatile("s_waitcnt vmcnt(0)" ::: "memory");
;         } else {
;             XB_SPIN(xb_ld(&bar[XB_XGEN(b.x)]) == gen, bar);
.LBB0_196:
	s_and_b32 s38, s33, 0xff
	s_mov_b64 s[36:37], -1
	s_cmp_lg_u32 s38, 0
	s_mov_b64 s[40:41], -1
	s_cbranch_scc0 .LBB0_199
	s_and_b64 vcc, exec, s[40:41]
	s_cbranch_vccz .LBB0_195

; __device__ __forceinline__ unsigned xb_ld(unsigned* p)              { return __hip_atomic_load(p, __ATOMIC_RELAXED, __HIP_MEMORY_SCOPE_AGENT); }
; __device__ __forceinline__ unsigned xb_add(unsigned* p, unsigned v) { return __hip_atomic_fetch_add(p, v, __ATOMIC_RELAXED, __HIP_MEMORY_SCOPE_AGENT); }
; #define XB_SPIN(cond, bar) do { unsigned _sp = 0; while (cond) { __builtin_amdgcn_s_sleep(1); \
;     if ((++_sp & 255u) == 0u) { if (xb_ld(&(bar)[XB_TMO])) break; if (_sp > XB_SPIN_CAP) { atomicAdd(&(bar)[XB_TMO], 1u); break; } } } } while (0)
; __device__ __forceinline__ void xcd_barrier(const XcdBarrier& b) {
;     ...
;             else XB_SPIN(xb_ld(&bar[XB_TOPGEN]) == tg, bar);
;             __builtin_amdgcn_fence(__ATOMIC_ACQUIRE, "agent");
;             xb_add(&bar[XB_XGEN(b.x)], 1u);
;             asm volatile("s_waitcnt vmcnt(0)" ::: "memory");
;         } else {
;             XB_SPIN(xb_ld(&bar[XB_XGEN(b.x)]) == gen, bar);
.LBB0_213:
	s_and_b32 s36, s33, 0xff
	s_cmp_lg_u32 s36, 0
	s_mov_b64 s[38:39], -1
	s_cbranch_scc0 .LBB0_216
	s_mov_b64 s[40:41], -1
	s_and_b64 vcc, exec, s[38:39]
	s_cbranch_vccz .LBB0_212

; __device__ __forceinline__ unsigned xb_ld(unsigned* p)              { return __hip_atomic_load(p, __ATOMIC_RELAXED, __HIP_MEMORY_SCOPE_AGENT); }
; __device__ __forceinline__ void xcd_barrier_complete(unsigned* bar, unsigned x, unsigned& nloc, unsigned& nx) {
;     ...
;     for (;;) {
;         sum = 0u; cnt = 0u; mine = 0u;
; #pragma unroll
;         for (unsigned j = 0; j < 16; ++j) { const unsigned c = xb_ld(&bar[XB_XCNT(j)]); sum += c; cnt += (c > 0u) ? 1u : 0u; mine = (j == x) ? c : mine; }
;         if (sum == G) break;
;         __builtin_amdgcn_s_sleep(1);
;         if ((++sp & 255u) == 0u) { if (xb_ld(&bar[XB_TMO])) break; if (sp > XB_SPIN_CAP) { atomicAdd(&bar[XB_TMO], 1u); break; } }
;     }
.LBB0_257:
	global_load_dword v15, v16, s[8:9] sc1
	global_load_dword v0, v16, s[10:11] sc1
	global_load_dword v1, v16, s[18:19] sc1
	global_load_dword v2, v16, s[30:31] sc1
	global_load_dword v3, v16, s[34:35] sc1
	global_load_dword v4, v16, s[36:37] sc1
	global_load_dword v5, v16, s[38:39] sc1
	global_load_dword v6, v16, s[40:41] sc1
	global_load_dword v7, v16, s[42:43] sc1
	global_load_dword v8, v16, s[44:45] sc1
	global_load_dword v9, v16, s[46:47] sc1
	global_load_dword v10, v16, s[48:49] sc1
	global_load_dword v11, v16, s[50:51] sc1
	global_load_dword v12, v16, s[52:53] sc1
	global_load_dword v13, v16, s[54:55] sc1
	global_load_dword v14, v16, s[56:57] sc1
	s_mov_b64 s[58:59], -1
	s_mov_b64 s[60:61], -1
	s_waitcnt vmcnt(14)
	v_add_u32_e32 v17, v0, v15
	s_waitcnt vmcnt(13)
	v_add_u32_e32 v17, v17, v1
	s_waitcnt vmcnt(12)
	v_add_u32_e32 v17, v17, v2
	s_waitcnt vmcnt(11)
	v_add_u32_e32 v17, v17, v3
	s_waitcnt vmcnt(10)
	v_add_u32_e32 v17, v17, v4
	s_waitcnt vmcnt(9)
	v_add_u32_e32 v17, v17, v5
	s_waitcnt vmcnt(8)
	v_add_u32_e32 v17, v17, v6
	s_waitcnt vmcnt(7)
	v_add_u32_e32 v17, v17, v7
	s_waitcnt vmcnt(6)
	v_add_u32_e32 v17, v17, v8
	s_waitcnt vmcnt(5)
	v_add_u32_e32 v17, v17, v9
	s_waitcnt vmcnt(4)
	v_add_u32_e32 v17, v17, v10
	s_waitcnt vmcnt(3)
	v_add_u32_e32 v17, v17, v11
	s_waitcnt vmcnt(2)
	v_add_u32_e32 v17, v17, v12
	s_waitcnt vmcnt(1)
	v_add_u32_e32 v17, v17, v13
	s_waitcnt vmcnt(0)
	v_add_u32_e32 v17, v17, v14
	v_cmp_eq_u32_e32 vcc, s64, v17
	s_cbranch_vccnz .LBB0_256
	s_and_b32 s16, s33, 0xff
	s_cmp_eq_u32 s16, 0
	s_mov_b64 s[62:63], -1
	s_cbranch_scc1 .LBB0_261
	s_and_b64 vcc, exec, s[62:63]
	s_cbranch_vccz .LBB0_256

; __device__ __forceinline__ unsigned xb_ld(unsigned* p)              { return __hip_atomic_load(p, __ATOMIC_RELAXED, __HIP_MEMORY_SCOPE_AGENT); }
; __device__ __forceinline__ unsigned xb_add(unsigned* p, unsigned v) { return __hip_atomic_fetch_add(p, v, __ATOMIC_RELAXED, __HIP_MEMORY_SCOPE_AGENT); }
; #define XB_SPIN(cond, bar) do { unsigned _sp = 0; while (cond) { __builtin_amdgcn_s_sleep(1); \
;     if ((++_sp & 255u) == 0u) { if (xb_ld(&(bar)[XB_TMO])) break; if (_sp > XB_SPIN_CAP) { atomicAdd(&(bar)[XB_TMO], 1u); break; } } } } while (0)
; __device__ __forceinline__ void xcd_barrier(const XcdBarrier& b) {
;     ...
;             else XB_SPIN(xb_ld(&bar[XB_TOPGEN]) == tg, bar);
;             __builtin_amdgcn_fence(__ATOMIC_ACQUIRE, "agent");
;             xb_add(&bar[XB_XGEN(b.x)], 1u);
;             asm volatile("s_waitcnt vmcnt(0)" ::: "memory");
;         } else {
;             XB_SPIN(xb_ld(&bar[XB_XGEN(b.x)]) == gen, bar);
.LBB0_275:
	s_and_b32 s16, s33, 0xff
	s_mov_b64 s[38:39], -1
	s_cmp_lg_u32 s16, 0
	s_mov_b64 s[42:43], -1
	s_cbranch_scc0 .LBB0_278
	s_and_b64 vcc, exec, s[42:43]
	s_cbranch_vccz .LBB0_274

; __device__ __forceinline__ unsigned xb_ld(unsigned* p)              { return __hip_atomic_load(p, __ATOMIC_RELAXED, __HIP_MEMORY_SCOPE_AGENT); }
; __device__ __forceinline__ unsigned xb_add(unsigned* p, unsigned v) { return __hip_atomic_fetch_add(p, v, __ATOMIC_RELAXED, __HIP_MEMORY_SCOPE_AGENT); }
; #define XB_SPIN(cond, bar) do { unsigned _sp = 0; while (cond) { __builtin_amdgcn_s_sleep(1); \
;     if ((++_sp & 255u) == 0u) { if (xb_ld(&(bar)[XB_TMO])) break; if (_sp > XB_SPIN_CAP) { atomicAdd(&(bar)[XB_TMO], 1u); break; } } } } while (0)
; __device__ __forceinline__ void xcd_barrier(const XcdBarrier& b) {
;     ...
;             else XB_SPIN(xb_ld(&bar[XB_TOPGEN]) == tg, bar);
;             __builtin_amdgcn_fence(__ATOMIC_ACQUIRE, "agent");
;             xb_add(&bar[XB_XGEN(b.x)], 1u);
;             asm volatile("s_waitcnt vmcnt(0)" ::: "memory");
;         } else {
;             XB_SPIN(xb_ld(&bar[XB_XGEN(b.x)]) == gen, bar);
.LBB0_292:
	s_and_b32 s16, s33, 0xff
	s_cmp_lg_u32 s16, 0
	s_mov_b64 s[40:41], -1
	s_cbranch_scc0 .LBB0_295
	s_mov_b64 s[42:43], -1
	s_and_b64 vcc, exec, s[40:41]
	s_cbranch_vccz .LBB0_291

; __device__ __forceinline__ unsigned xb_ld(unsigned* p)              { return __hip_atomic_load(p, __ATOMIC_RELAXED, __HIP_MEMORY_SCOPE_AGENT); }
; __device__ __forceinline__ void xcd_barrier_complete(unsigned* bar, unsigned x, unsigned& nloc, unsigned& nx) {
;     ...
;     for (;;) {
;         sum = 0u; cnt = 0u; mine = 0u;
; #pragma unroll
;         for (unsigned j = 0; j < 16; ++j) { const unsigned c = xb_ld(&bar[XB_XCNT(j)]); sum += c; cnt += (c > 0u) ? 1u : 0u; mine = (j == x) ? c : mine; }
;         if (sum == G) break;
;         __builtin_amdgcn_s_sleep(1);
;         if ((++sp & 255u) == 0u) { if (xb_ld(&bar[XB_TMO])) break; if (sp > XB_SPIN_CAP) { atomicAdd(&bar[XB_TMO], 1u); break; } }
;     }
.LBB0_319:
	global_load_dword v15, v16, s[8:9] sc1
	global_load_dword v0, v16, s[10:11] sc1
	global_load_dword v1, v16, s[12:13] sc1
	global_load_dword v2, v16, s[18:19] sc1
	global_load_dword v3, v16, s[30:31] sc1
	global_load_dword v4, v16, s[36:37] sc1
	global_load_dword v5, v16, s[38:39] sc1
	global_load_dword v6, v16, s[40:41] sc1
	global_load_dword v7, v16, s[42:43] sc1
	global_load_dword v8, v16, s[44:45] sc1
	global_load_dword v9, v16, s[46:47] sc1
	global_load_dword v10, v16, s[48:49] sc1
	global_load_dword v11, v16, s[50:51] sc1
	global_load_dword v12, v16, s[52:53] sc1
	global_load_dword v13, v16, s[54:55] sc1
	global_load_dword v14, v16, s[56:57] sc1
	s_mov_b64 s[58:59], -1
	s_mov_b64 s[60:61], -1
	s_waitcnt vmcnt(14)
	v_add_u32_e32 v17, v0, v15
	s_waitcnt vmcnt(13)
	v_add_u32_e32 v17, v17, v1
	s_waitcnt vmcnt(12)
	v_add_u32_e32 v17, v17, v2
	s_waitcnt vmcnt(11)
	v_add_u32_e32 v17, v17, v3
	s_waitcnt vmcnt(10)
	v_add_u32_e32 v17, v17, v4
	s_waitcnt vmcnt(9)
	v_add_u32_e32 v17, v17, v5
	s_waitcnt vmcnt(8)
	v_add_u32_e32 v17, v17, v6
	s_waitcnt vmcnt(7)
	v_add_u32_e32 v17, v17, v7
	s_waitcnt vmcnt(6)
	v_add_u32_e32 v17, v17, v8
	s_waitcnt vmcnt(5)
	v_add_u32_e32 v17, v17, v9
	s_waitcnt vmcnt(4)
	v_add_u32_e32 v17, v17, v10
	s_waitcnt vmcnt(3)
	v_add_u32_e32 v17, v17, v11
	s_waitcnt vmcnt(2)
	v_add_u32_e32 v17, v17, v12
	s_waitcnt vmcnt(1)
	v_add_u32_e32 v17, v17, v13
	s_waitcnt vmcnt(0)
	v_add_u32_e32 v17, v17, v14
	v_cmp_eq_u32_e32 vcc, s64, v17
	s_cbranch_vccnz .LBB0_318
	s_and_b32 s16, s33, 0xff
	s_cmp_eq_u32 s16, 0
	s_mov_b64 s[62:63], -1
	s_cbranch_scc1 .LBB0_323
	s_and_b64 vcc, exec, s[62:63]
	s_cbranch_vccz .LBB0_318

; __device__ __forceinline__ unsigned xb_ld(unsigned* p)              { return __hip_atomic_load(p, __ATOMIC_RELAXED, __HIP_MEMORY_SCOPE_AGENT); }
; __device__ __forceinline__ void xcd_barrier_complete(unsigned* bar, unsigned x, unsigned& nloc, unsigned& nx) {
;     ...
;     for (;;) {
;         sum = 0u; cnt = 0u; mine = 0u;
; #pragma unroll
;         for (unsigned j = 0; j < 16; ++j) { const unsigned c = xb_ld(&bar[XB_XCNT(j)]); sum += c; cnt += (c > 0u) ? 1u : 0u; mine = (j == x) ? c : mine; }
;         if (sum == G) break;
;         __builtin_amdgcn_s_sleep(1);
;         if ((++sp & 255u) == 0u) { if (xb_ld(&bar[XB_TMO])) break; if (sp > XB_SPIN_CAP) { atomicAdd(&bar[XB_TMO], 1u); break; } }
;     }
.LBB0_546:
	global_load_dword v15, v16, s[8:9] sc1
	global_load_dword v0, v16, s[10:11] sc1
	global_load_dword v1, v16, s[12:13] sc1
	global_load_dword v2, v16, s[18:19] sc1
	global_load_dword v3, v16, s[36:37] sc1
	global_load_dword v4, v16, s[38:39] sc1
	global_load_dword v5, v16, s[40:41] sc1
	global_load_dword v6, v16, s[42:43] sc1
	global_load_dword v7, v16, s[44:45] sc1
	global_load_dword v8, v16, s[46:47] sc1
	global_load_dword v9, v16, s[48:49] sc1
	global_load_dword v10, v16, s[50:51] sc1
	global_load_dword v11, v16, s[52:53] sc1
	global_load_dword v12, v16, s[54:55] sc1
	global_load_dword v13, v16, s[56:57] sc1
	global_load_dword v14, v16, s[58:59] sc1
	s_mov_b64 s[60:61], -1
	s_mov_b64 s[62:63], -1
	s_waitcnt vmcnt(14)
	v_add_u32_e32 v17, v0, v15
	s_waitcnt vmcnt(13)
	v_add_u32_e32 v17, v17, v1
	s_waitcnt vmcnt(12)
	v_add_u32_e32 v17, v17, v2
	s_waitcnt vmcnt(11)
	v_add_u32_e32 v17, v17, v3
	s_waitcnt vmcnt(10)
	v_add_u32_e32 v17, v17, v4
	s_waitcnt vmcnt(9)
	v_add_u32_e32 v17, v17, v5
	s_waitcnt vmcnt(8)
	v_add_u32_e32 v17, v17, v6
	s_waitcnt vmcnt(7)
	v_add_u32_e32 v17, v17, v7
	s_waitcnt vmcnt(6)
	v_add_u32_e32 v17, v17, v8
	s_waitcnt vmcnt(5)
	v_add_u32_e32 v17, v17, v9
	s_waitcnt vmcnt(4)
	v_add_u32_e32 v17, v17, v10
	s_waitcnt vmcnt(3)
	v_add_u32_e32 v17, v17, v11
	s_waitcnt vmcnt(2)
	v_add_u32_e32 v17, v17, v12
	s_waitcnt vmcnt(1)
	v_add_u32_e32 v17, v17, v13
	s_waitcnt vmcnt(0)
	v_add_u32_e32 v17, v17, v14
	v_cmp_eq_u32_e32 vcc, s66, v17
	s_cbranch_vccnz .LBB0_545
	s_and_b32 s16, s33, 0xff
	s_cmp_eq_u32 s16, 0
	s_mov_b64 s[64:65], -1
	s_cbranch_scc1 .LBB0_550
	s_and_b64 vcc, exec, s[64:65]
	s_cbranch_vccz .LBB0_545

; __device__ __forceinline__ unsigned xb_ld(unsigned* p)              { return __hip_atomic_load(p, __ATOMIC_RELAXED, __HIP_MEMORY_SCOPE_AGENT); }
; __device__ __forceinline__ unsigned xb_add(unsigned* p, unsigned v) { return __hip_atomic_fetch_add(p, v, __ATOMIC_RELAXED, __HIP_MEMORY_SCOPE_AGENT); }
; #define XB_SPIN(cond, bar) do { unsigned _sp = 0; while (cond) { __builtin_amdgcn_s_sleep(1); \
;     if ((++_sp & 255u) == 0u) { if (xb_ld(&(bar)[XB_TMO])) break; if (_sp > XB_SPIN_CAP) { atomicAdd(&(bar)[XB_TMO], 1u); break; } } } } while (0)
; __device__ __forceinline__ void xcd_barrier(const XcdBarrier& b) {
;     ...
;             else XB_SPIN(xb_ld(&bar[XB_TOPGEN]) == tg, bar);
;             __builtin_amdgcn_fence(__ATOMIC_ACQUIRE, "agent");
;             xb_add(&bar[XB_XGEN(b.x)], 1u);
;             asm volatile("s_waitcnt vmcnt(0)" ::: "memory");
;         } else {
;             XB_SPIN(xb_ld(&bar[XB_XGEN(b.x)]) == gen, bar);
.LBB0_564:
	s_and_b32 s16, s33, 0xff
	s_mov_b64 s[40:41], -1
	s_cmp_lg_u32 s16, 0
	s_mov_b64 s[44:45], -1
	s_cbranch_scc0 .LBB0_567
	s_and_b64 vcc, exec, s[44:45]
	s_cbranch_vccz .LBB0_563

; __device__ __forceinline__ unsigned xb_ld(unsigned* p)              { return __hip_atomic_load(p, __ATOMIC_RELAXED, __HIP_MEMORY_SCOPE_AGENT); }
; __device__ __forceinline__ unsigned xb_add(unsigned* p, unsigned v) { return __hip_atomic_fetch_add(p, v, __ATOMIC_RELAXED, __HIP_MEMORY_SCOPE_AGENT); }
; #define XB_SPIN(cond, bar) do { unsigned _sp = 0; while (cond) { __builtin_amdgcn_s_sleep(1); \
;     if ((++_sp & 255u) == 0u) { if (xb_ld(&(bar)[XB_TMO])) break; if (_sp > XB_SPIN_CAP) { atomicAdd(&(bar)[XB_TMO], 1u); break; } } } } while (0)
; __device__ __forceinline__ void xcd_barrier(const XcdBarrier& b) {
;     ...
;             else XB_SPIN(xb_ld(&bar[XB_TOPGEN]) == tg, bar);
;             __builtin_amdgcn_fence(__ATOMIC_ACQUIRE, "agent");
;             xb_add(&bar[XB_XGEN(b.x)], 1u);
;             asm volatile("s_waitcnt vmcnt(0)" ::: "memory");
;         } else {
;             XB_SPIN(xb_ld(&bar[XB_XGEN(b.x)]) == gen, bar);
.LBB0_581:
	s_and_b32 s16, s33, 0xff
	s_cmp_lg_u32 s16, 0
	s_mov_b64 s[42:43], -1
	s_cbranch_scc0 .LBB0_584
	s_mov_b64 s[44:45], -1
	s_and_b64 vcc, exec, s[42:43]
	s_cbranch_vccz .LBB0_580

; __device__ __forceinline__ unsigned xb_ld(unsigned* p)              { return __hip_atomic_load(p, __ATOMIC_RELAXED, __HIP_MEMORY_SCOPE_AGENT); }
; __device__ __forceinline__ void xcd_barrier_complete(unsigned* bar, unsigned x, unsigned& nloc, unsigned& nx) {
;     ...
;     for (;;) {
;         sum = 0u; cnt = 0u; mine = 0u;
; #pragma unroll
;         for (unsigned j = 0; j < 16; ++j) { const unsigned c = xb_ld(&bar[XB_XCNT(j)]); sum += c; cnt += (c > 0u) ? 1u : 0u; mine = (j == x) ? c : mine; }
;         if (sum == G) break;
;         __builtin_amdgcn_s_sleep(1);
;         if ((++sp & 255u) == 0u) { if (xb_ld(&bar[XB_TMO])) break; if (sp > XB_SPIN_CAP) { atomicAdd(&bar[XB_TMO], 1u); break; } }
;     }
.LBB0_669:
	global_load_dword v15, v16, s[10:11] sc1
	global_load_dword v0, v16, s[12:13] sc1
	global_load_dword v1, v16, s[16:17] sc1
	global_load_dword v2, v16, s[18:19] sc1
	global_load_dword v3, v16, s[36:37] sc1
	global_load_dword v4, v16, s[38:39] sc1
	global_load_dword v5, v16, s[40:41] sc1
	global_load_dword v6, v16, s[42:43] sc1
	global_load_dword v7, v16, s[44:45] sc1
	global_load_dword v8, v16, s[46:47] sc1
	global_load_dword v9, v16, s[48:49] sc1
	global_load_dword v10, v16, s[50:51] sc1
	global_load_dword v11, v16, s[52:53] sc1
	global_load_dword v12, v16, s[54:55] sc1
	global_load_dword v13, v16, s[56:57] sc1
	global_load_dword v14, v16, s[58:59] sc1
	s_mov_b64 s[60:61], -1
	s_mov_b64 s[62:63], -1
	s_waitcnt vmcnt(14)
	v_add_u32_e32 v17, v0, v15
	s_waitcnt vmcnt(13)
	v_add_u32_e32 v17, v17, v1
	s_waitcnt vmcnt(12)
	v_add_u32_e32 v17, v17, v2
	s_waitcnt vmcnt(11)
	v_add_u32_e32 v17, v17, v3
	s_waitcnt vmcnt(10)
	v_add_u32_e32 v17, v17, v4
	s_waitcnt vmcnt(9)
	v_add_u32_e32 v17, v17, v5
	s_waitcnt vmcnt(8)
	v_add_u32_e32 v17, v17, v6
	s_waitcnt vmcnt(7)
	v_add_u32_e32 v17, v17, v7
	s_waitcnt vmcnt(6)
	v_add_u32_e32 v17, v17, v8
	s_waitcnt vmcnt(5)
	v_add_u32_e32 v17, v17, v9
	s_waitcnt vmcnt(4)
	v_add_u32_e32 v17, v17, v10
	s_waitcnt vmcnt(3)
	v_add_u32_e32 v17, v17, v11
	s_waitcnt vmcnt(2)
	v_add_u32_e32 v17, v17, v12
	s_waitcnt vmcnt(1)
	v_add_u32_e32 v17, v17, v13
	s_waitcnt vmcnt(0)
	v_add_u32_e32 v17, v17, v14
	v_cmp_eq_u32_e32 vcc, s66, v17
	s_cbranch_vccnz .LBB0_668
	s_and_b32 s60, s33, 0xff
	s_cmp_eq_u32 s60, 0
	s_mov_b64 s[60:61], -1
	s_mov_b64 s[64:65], -1
	s_cbranch_scc1 .LBB0_673
	s_and_b64 vcc, exec, s[64:65]
	s_cbranch_vccz .LBB0_668

; __device__ __forceinline__ unsigned xb_ld(unsigned* p)              { return __hip_atomic_load(p, __ATOMIC_RELAXED, __HIP_MEMORY_SCOPE_AGENT); }
; __device__ __forceinline__ unsigned xb_add(unsigned* p, unsigned v) { return __hip_atomic_fetch_add(p, v, __ATOMIC_RELAXED, __HIP_MEMORY_SCOPE_AGENT); }
; #define XB_SPIN(cond, bar) do { unsigned _sp = 0; while (cond) { __builtin_amdgcn_s_sleep(1); \
;     if ((++_sp & 255u) == 0u) { if (xb_ld(&(bar)[XB_TMO])) break; if (_sp > XB_SPIN_CAP) { atomicAdd(&(bar)[XB_TMO], 1u); break; } } } } while (0)
; __device__ __forceinline__ void xcd_barrier(const XcdBarrier& b) {
;     ...
;             else XB_SPIN(xb_ld(&bar[XB_TOPGEN]) == tg, bar);
;             __builtin_amdgcn_fence(__ATOMIC_ACQUIRE, "agent");
;             xb_add(&bar[XB_XGEN(b.x)], 1u);
;             asm volatile("s_waitcnt vmcnt(0)" ::: "memory");
;         } else {
;             XB_SPIN(xb_ld(&bar[XB_XGEN(b.x)]) == gen, bar);
.LBB0_687:
	s_and_b32 s42, s33, 0xff
	s_mov_b64 s[40:41], -1
	s_cmp_lg_u32 s42, 0
	s_mov_b64 s[44:45], -1
	s_cbranch_scc0 .LBB0_690
	s_and_b64 vcc, exec, s[44:45]
	s_cbranch_vccz .LBB0_686

; __device__ __forceinline__ unsigned xb_ld(unsigned* p)              { return __hip_atomic_load(p, __ATOMIC_RELAXED, __HIP_MEMORY_SCOPE_AGENT); }
; __device__ __forceinline__ unsigned xb_add(unsigned* p, unsigned v) { return __hip_atomic_fetch_add(p, v, __ATOMIC_RELAXED, __HIP_MEMORY_SCOPE_AGENT); }
; #define XB_SPIN(cond, bar) do { unsigned _sp = 0; while (cond) { __builtin_amdgcn_s_sleep(1); \
;     if ((++_sp & 255u) == 0u) { if (xb_ld(&(bar)[XB_TMO])) break; if (_sp > XB_SPIN_CAP) { atomicAdd(&(bar)[XB_TMO], 1u); break; } } } } while (0)
; __device__ __forceinline__ void xcd_barrier(const XcdBarrier& b) {
;     ...
;             else XB_SPIN(xb_ld(&bar[XB_TOPGEN]) == tg, bar);
;             __builtin_amdgcn_fence(__ATOMIC_ACQUIRE, "agent");
;             xb_add(&bar[XB_XGEN(b.x)], 1u);
;             asm volatile("s_waitcnt vmcnt(0)" ::: "memory");
;         } else {
;             XB_SPIN(xb_ld(&bar[XB_XGEN(b.x)]) == gen, bar);
.LBB0_704:
	s_and_b32 s40, s33, 0xff
	s_cmp_lg_u32 s40, 0
	s_mov_b64 s[42:43], -1
	s_cbranch_scc0 .LBB0_707
	s_mov_b64 s[44:45], -1
	s_and_b64 vcc, exec, s[42:43]
	s_cbranch_vccz .LBB0_703

; __device__ __forceinline__ unsigned xb_ld(unsigned* p)              { return __hip_atomic_load(p, __ATOMIC_RELAXED, __HIP_MEMORY_SCOPE_AGENT); }
; __device__ __forceinline__ void xcd_barrier_complete(unsigned* bar, unsigned x, unsigned& nloc, unsigned& nx) {
;     ...
;     for (;;) {
;         sum = 0u; cnt = 0u; mine = 0u;
; #pragma unroll
;         for (unsigned j = 0; j < 16; ++j) { const unsigned c = xb_ld(&bar[XB_XCNT(j)]); sum += c; cnt += (c > 0u) ? 1u : 0u; mine = (j == x) ? c : mine; }
;         if (sum == G) break;
;         __builtin_amdgcn_s_sleep(1);
;         if ((++sp & 255u) == 0u) { if (xb_ld(&bar[XB_TMO])) break; if (sp > XB_SPIN_CAP) { atomicAdd(&bar[XB_TMO], 1u); break; } }
;     }
.LBB0_742:
	global_load_dword v15, v16, s[10:11] sc1
	global_load_dword v0, v16, s[16:17] sc1
	global_load_dword v1, v16, s[18:19] sc1
	global_load_dword v2, v16, s[36:37] sc1
	global_load_dword v3, v16, s[38:39] sc1
	global_load_dword v4, v16, s[40:41] sc1
	global_load_dword v5, v16, s[42:43] sc1
	global_load_dword v6, v16, s[44:45] sc1
	global_load_dword v7, v16, s[46:47] sc1
	global_load_dword v8, v16, s[48:49] sc1
	global_load_dword v9, v16, s[50:51] sc1
	global_load_dword v10, v16, s[52:53] sc1
	global_load_dword v11, v16, s[54:55] sc1
	global_load_dword v12, v16, s[56:57] sc1
	global_load_dword v13, v16, s[58:59] sc1
	global_load_dword v14, v16, s[60:61] sc1
	s_mov_b64 s[62:63], -1
	s_mov_b64 s[64:65], -1
	s_waitcnt vmcnt(14)
	v_add_u32_e32 v17, v0, v15
	s_waitcnt vmcnt(13)
	v_add_u32_e32 v17, v17, v1
	s_waitcnt vmcnt(12)
	v_add_u32_e32 v17, v17, v2
	s_waitcnt vmcnt(11)
	v_add_u32_e32 v17, v17, v3
	s_waitcnt vmcnt(10)
	v_add_u32_e32 v17, v17, v4
	s_waitcnt vmcnt(9)
	v_add_u32_e32 v17, v17, v5
	s_waitcnt vmcnt(8)
	v_add_u32_e32 v17, v17, v6
	s_waitcnt vmcnt(7)
	v_add_u32_e32 v17, v17, v7
	s_waitcnt vmcnt(6)
	v_add_u32_e32 v17, v17, v8
	s_waitcnt vmcnt(5)
	v_add_u32_e32 v17, v17, v9
	s_waitcnt vmcnt(4)
	v_add_u32_e32 v17, v17, v10
	s_waitcnt vmcnt(3)
	v_add_u32_e32 v17, v17, v11
	s_waitcnt vmcnt(2)
	v_add_u32_e32 v17, v17, v12
	s_waitcnt vmcnt(1)
	v_add_u32_e32 v17, v17, v13
	s_waitcnt vmcnt(0)
	v_add_u32_e32 v17, v17, v14
	v_cmp_eq_u32_e32 vcc, s68, v17
	s_cbranch_vccnz .LBB0_741
	s_and_b32 s62, s33, 0xff
	s_cmp_eq_u32 s62, 0
	s_mov_b64 s[62:63], -1
	s_mov_b64 s[66:67], -1
	s_cbranch_scc1 .LBB0_746
	s_and_b64 vcc, exec, s[66:67]
	s_cbranch_vccz .LBB0_741

; __device__ __forceinline__ unsigned xb_ld(unsigned* p)              { return __hip_atomic_load(p, __ATOMIC_RELAXED, __HIP_MEMORY_SCOPE_AGENT); }
; __device__ __forceinline__ unsigned xb_add(unsigned* p, unsigned v) { return __hip_atomic_fetch_add(p, v, __ATOMIC_RELAXED, __HIP_MEMORY_SCOPE_AGENT); }
; #define XB_SPIN(cond, bar) do { unsigned _sp = 0; while (cond) { __builtin_amdgcn_s_sleep(1); \
;     if ((++_sp & 255u) == 0u) { if (xb_ld(&(bar)[XB_TMO])) break; if (_sp > XB_SPIN_CAP) { atomicAdd(&(bar)[XB_TMO], 1u); break; } } } } while (0)
; __device__ __forceinline__ void xcd_barrier(const XcdBarrier& b) {
;     ...
;             else XB_SPIN(xb_ld(&bar[XB_TOPGEN]) == tg, bar);
;             __builtin_amdgcn_fence(__ATOMIC_ACQUIRE, "agent");
;             xb_add(&bar[XB_XGEN(b.x)], 1u);
;             asm volatile("s_waitcnt vmcnt(0)" ::: "memory");
;         } else {
;             XB_SPIN(xb_ld(&bar[XB_XGEN(b.x)]) == gen, bar);
.LBB0_760:
	s_and_b32 s44, s33, 0xff
	s_mov_b64 s[42:43], -1
	s_cmp_lg_u32 s44, 0
	s_mov_b64 s[46:47], -1
	s_cbranch_scc0 .LBB0_763
	s_and_b64 vcc, exec, s[46:47]
	s_cbranch_vccz .LBB0_759

; __device__ __forceinline__ unsigned xb_ld(unsigned* p)              { return __hip_atomic_load(p, __ATOMIC_RELAXED, __HIP_MEMORY_SCOPE_AGENT); }
; __device__ __forceinline__ unsigned xb_add(unsigned* p, unsigned v) { return __hip_atomic_fetch_add(p, v, __ATOMIC_RELAXED, __HIP_MEMORY_SCOPE_AGENT); }
; #define XB_SPIN(cond, bar) do { unsigned _sp = 0; while (cond) { __builtin_amdgcn_s_sleep(1); \
;     if ((++_sp & 255u) == 0u) { if (xb_ld(&(bar)[XB_TMO])) break; if (_sp > XB_SPIN_CAP) { atomicAdd(&(bar)[XB_TMO], 1u); break; } } } } while (0)
; __device__ __forceinline__ void xcd_barrier(const XcdBarrier& b) {
;     ...
;             else XB_SPIN(xb_ld(&bar[XB_TOPGEN]) == tg, bar);
;             __builtin_amdgcn_fence(__ATOMIC_ACQUIRE, "agent");
;             xb_add(&bar[XB_XGEN(b.x)], 1u);
;             asm volatile("s_waitcnt vmcnt(0)" ::: "memory");
;         } else {
;             XB_SPIN(xb_ld(&bar[XB_XGEN(b.x)]) == gen, bar);
.LBB0_777:
	s_and_b32 s42, s33, 0xff
	s_cmp_lg_u32 s42, 0
	s_mov_b64 s[44:45], -1
	s_cbranch_scc0 .LBB0_780
	s_mov_b64 s[46:47], -1
	s_and_b64 vcc, exec, s[44:45]
	s_cbranch_vccz .LBB0_776

; __device__ __forceinline__ unsigned xb_ld(unsigned* p)              { return __hip_atomic_load(p, __ATOMIC_RELAXED, __HIP_MEMORY_SCOPE_AGENT); }
; __device__ __forceinline__ void xcd_barrier_complete(unsigned* bar, unsigned x, unsigned& nloc, unsigned& nx) {
;     ...
;     for (;;) {
;         sum = 0u; cnt = 0u; mine = 0u;
; #pragma unroll
;         for (unsigned j = 0; j < 16; ++j) { const unsigned c = xb_ld(&bar[XB_XCNT(j)]); sum += c; cnt += (c > 0u) ? 1u : 0u; mine = (j == x) ? c : mine; }
;         if (sum == G) break;
;         __builtin_amdgcn_s_sleep(1);
;         if ((++sp & 255u) == 0u) { if (xb_ld(&bar[XB_TMO])) break; if (sp > XB_SPIN_CAP) { atomicAdd(&bar[XB_TMO], 1u); break; } }
;     }
.LBB0_1035:
	global_load_dword v15, v16, s[10:11] sc1
	global_load_dword v0, v16, s[16:17] sc1
	global_load_dword v1, v16, s[18:19] sc1
	global_load_dword v2, v16, s[34:35] sc1
	global_load_dword v3, v16, s[36:37] sc1
	global_load_dword v4, v16, s[38:39] sc1
	global_load_dword v5, v16, s[40:41] sc1
	global_load_dword v6, v16, s[42:43] sc1
	global_load_dword v7, v16, s[44:45] sc1
	global_load_dword v8, v16, s[46:47] sc1
	global_load_dword v9, v16, s[48:49] sc1
	global_load_dword v10, v16, s[50:51] sc1
	global_load_dword v11, v16, s[52:53] sc1
	global_load_dword v12, v16, s[54:55] sc1
	global_load_dword v13, v16, s[56:57] sc1
	global_load_dword v14, v16, s[58:59] sc1
	s_mov_b64 s[60:61], -1
	s_mov_b64 s[62:63], -1
	s_waitcnt vmcnt(14)
	v_add_u32_e32 v17, v0, v15
	s_waitcnt vmcnt(13)
	v_add_u32_e32 v17, v17, v1
	s_waitcnt vmcnt(12)
	v_add_u32_e32 v17, v17, v2
	s_waitcnt vmcnt(11)
	v_add_u32_e32 v17, v17, v3
	s_waitcnt vmcnt(10)
	v_add_u32_e32 v17, v17, v4
	s_waitcnt vmcnt(9)
	v_add_u32_e32 v17, v17, v5
	s_waitcnt vmcnt(8)
	v_add_u32_e32 v17, v17, v6
	s_waitcnt vmcnt(7)
	v_add_u32_e32 v17, v17, v7
	s_waitcnt vmcnt(6)
	v_add_u32_e32 v17, v17, v8
	s_waitcnt vmcnt(5)
	v_add_u32_e32 v17, v17, v9
	s_waitcnt vmcnt(4)
	v_add_u32_e32 v17, v17, v10
	s_waitcnt vmcnt(3)
	v_add_u32_e32 v17, v17, v11
	s_waitcnt vmcnt(2)
	v_add_u32_e32 v17, v17, v12
	s_waitcnt vmcnt(1)
	v_add_u32_e32 v17, v17, v13
	s_waitcnt vmcnt(0)
	v_add_u32_e32 v17, v17, v14
	v_cmp_eq_u32_e32 vcc, s66, v17
	s_cbranch_vccnz .LBB0_1034
	s_and_b32 s60, s33, 0xff
	s_cmp_eq_u32 s60, 0
	s_mov_b64 s[60:61], -1
	s_mov_b64 s[64:65], -1
	s_cbranch_scc1 .LBB0_1039
	s_and_b64 vcc, exec, s[64:65]
	s_cbranch_vccz .LBB0_1034

; __device__ __forceinline__ unsigned xb_ld(unsigned* p)              { return __hip_atomic_load(p, __ATOMIC_RELAXED, __HIP_MEMORY_SCOPE_AGENT); }
; __device__ __forceinline__ void xcd_barrier_complete(unsigned* bar, unsigned x, unsigned& nloc, unsigned& nx) {
;     ...
;     for (;;) {
;         sum = 0u; cnt = 0u; mine = 0u;
; #pragma unroll
;         for (unsigned j = 0; j < 16; ++j) { const unsigned c = xb_ld(&bar[XB_XCNT(j)]); sum += c; cnt += (c > 0u) ? 1u : 0u; mine = (j == x) ? c : mine; }
;         if (sum == G) break;
;         __builtin_amdgcn_s_sleep(1);
;         if ((++sp & 255u) == 0u) { if (xb_ld(&bar[XB_TMO])) break; if (sp > XB_SPIN_CAP) { atomicAdd(&bar[XB_TMO], 1u); break; } }
;     }
.LBB0_1178:
	global_load_dword v15, v16, s[10:11] sc1
	global_load_dword v0, v16, s[16:17] sc1
	global_load_dword v1, v16, s[18:19] sc1
	global_load_dword v2, v16, s[26:27] sc1
	global_load_dword v3, v16, s[28:29] sc1
	global_load_dword v4, v16, s[30:31] sc1
	global_load_dword v5, v16, s[34:35] sc1
	global_load_dword v6, v16, s[36:37] sc1
	global_load_dword v7, v16, s[38:39] sc1
	global_load_dword v8, v16, s[40:41] sc1
	global_load_dword v9, v16, s[42:43] sc1
	global_load_dword v10, v16, s[44:45] sc1
	global_load_dword v11, v16, s[46:47] sc1
	global_load_dword v12, v16, s[48:49] sc1
	global_load_dword v13, v16, s[50:51] sc1
	global_load_dword v14, v16, s[52:53] sc1
	s_mov_b64 s[54:55], -1
	s_mov_b64 s[56:57], -1
	s_waitcnt vmcnt(14)
	v_add_u32_e32 v17, v0, v15
	s_waitcnt vmcnt(13)
	v_add_u32_e32 v17, v17, v1
	s_waitcnt vmcnt(12)
	v_add_u32_e32 v17, v17, v2
	s_waitcnt vmcnt(11)
	v_add_u32_e32 v17, v17, v3
	s_waitcnt vmcnt(10)
	v_add_u32_e32 v17, v17, v4
	s_waitcnt vmcnt(9)
	v_add_u32_e32 v17, v17, v5
	s_waitcnt vmcnt(8)
	v_add_u32_e32 v17, v17, v6
	s_waitcnt vmcnt(7)
	v_add_u32_e32 v17, v17, v7
	s_waitcnt vmcnt(6)
	v_add_u32_e32 v17, v17, v8
	s_waitcnt vmcnt(5)
	v_add_u32_e32 v17, v17, v9
	s_waitcnt vmcnt(4)
	v_add_u32_e32 v17, v17, v10
	s_waitcnt vmcnt(3)
	v_add_u32_e32 v17, v17, v11
	s_waitcnt vmcnt(2)
	v_add_u32_e32 v17, v17, v12
	s_waitcnt vmcnt(1)
	v_add_u32_e32 v17, v17, v13
	s_waitcnt vmcnt(0)
	v_add_u32_e32 v17, v17, v14
	v_cmp_eq_u32_e32 vcc, s60, v17
	s_cbranch_vccnz .LBB0_1177
	s_and_b32 s54, s33, 0xff
	s_cmp_eq_u32 s54, 0
	s_mov_b64 s[54:55], -1
	s_mov_b64 s[58:59], -1
	s_cbranch_scc1 .LBB0_1182
	s_and_b64 vcc, exec, s[58:59]
	s_cbranch_vccz .LBB0_1177

; __device__ __forceinline__ unsigned xb_ld(unsigned* p)              { return __hip_atomic_load(p, __ATOMIC_RELAXED, __HIP_MEMORY_SCOPE_AGENT); }
; __device__ __forceinline__ unsigned xb_add(unsigned* p, unsigned v) { return __hip_atomic_fetch_add(p, v, __ATOMIC_RELAXED, __HIP_MEMORY_SCOPE_AGENT); }
; #define XB_SPIN(cond, bar) do { unsigned _sp = 0; while (cond) { __builtin_amdgcn_s_sleep(1); \
;     if ((++_sp & 255u) == 0u) { if (xb_ld(&(bar)[XB_TMO])) break; if (_sp > XB_SPIN_CAP) { atomicAdd(&(bar)[XB_TMO], 1u); break; } } } } while (0)
; __device__ __forceinline__ void xcd_barrier(const XcdBarrier& b) {
;     ...
;             else XB_SPIN(xb_ld(&bar[XB_TOPGEN]) == tg, bar);
;             __builtin_amdgcn_fence(__ATOMIC_ACQUIRE, "agent");
;             xb_add(&bar[XB_XGEN(b.x)], 1u);
;             asm volatile("s_waitcnt vmcnt(0)" ::: "memory");
;         } else {
;             XB_SPIN(xb_ld(&bar[XB_XGEN(b.x)]) == gen, bar);
.LBB0_1196:
	s_and_b32 s36, s33, 0xff
	s_mov_b64 s[34:35], -1
	s_cmp_lg_u32 s36, 0
	s_mov_b64 s[38:39], -1
	s_cbranch_scc0 .LBB0_1199
	s_and_b64 vcc, exec, s[38:39]
	s_cbranch_vccz .LBB0_1195

; __device__ __forceinline__ unsigned xb_ld(unsigned* p)              { return __hip_atomic_load(p, __ATOMIC_RELAXED, __HIP_MEMORY_SCOPE_AGENT); }
; __device__ __forceinline__ unsigned xb_add(unsigned* p, unsigned v) { return __hip_atomic_fetch_add(p, v, __ATOMIC_RELAXED, __HIP_MEMORY_SCOPE_AGENT); }
; #define XB_SPIN(cond, bar) do { unsigned _sp = 0; while (cond) { __builtin_amdgcn_s_sleep(1); \
;     if ((++_sp & 255u) == 0u) { if (xb_ld(&(bar)[XB_TMO])) break; if (_sp > XB_SPIN_CAP) { atomicAdd(&(bar)[XB_TMO], 1u); break; } } } } while (0)
; __device__ __forceinline__ void xcd_barrier(const XcdBarrier& b) {
;     ...
;             else XB_SPIN(xb_ld(&bar[XB_TOPGEN]) == tg, bar);
;             __builtin_amdgcn_fence(__ATOMIC_ACQUIRE, "agent");
;             xb_add(&bar[XB_XGEN(b.x)], 1u);
;             asm volatile("s_waitcnt vmcnt(0)" ::: "memory");
;         } else {
;             XB_SPIN(xb_ld(&bar[XB_XGEN(b.x)]) == gen, bar);
.LBB0_1213:
	s_and_b32 s34, s33, 0xff
	s_cmp_lg_u32 s34, 0
	s_mov_b64 s[36:37], -1
	s_cbranch_scc0 .LBB0_1216
	s_mov_b64 s[38:39], -1
	s_and_b64 vcc, exec, s[36:37]
	s_cbranch_vccz .LBB0_1212

; __device__ __forceinline__ unsigned xb_ld(unsigned* p)              { return __hip_atomic_load(p, __ATOMIC_RELAXED, __HIP_MEMORY_SCOPE_AGENT); }
; __device__ __forceinline__ void xcd_barrier_complete(unsigned* bar, unsigned x, unsigned& nloc, unsigned& nx) {
;     ...
;     for (;;) {
;         sum = 0u; cnt = 0u; mine = 0u;
; #pragma unroll
;         for (unsigned j = 0; j < 16; ++j) { const unsigned c = xb_ld(&bar[XB_XCNT(j)]); sum += c; cnt += (c > 0u) ? 1u : 0u; mine = (j == x) ? c : mine; }
;         if (sum == G) break;
;         __builtin_amdgcn_s_sleep(1);
;         if ((++sp & 255u) == 0u) { if (xb_ld(&bar[XB_TMO])) break; if (sp > XB_SPIN_CAP) { atomicAdd(&bar[XB_TMO], 1u); break; } }
;     }
.LBB0_1374:
	global_load_dword v15, v16, s[10:11] sc1
	global_load_dword v0, v16, s[12:13] sc1
	global_load_dword v1, v16, s[16:17] sc1
	global_load_dword v2, v16, s[18:19] sc1
	global_load_dword v3, v16, s[26:27] sc1
	global_load_dword v4, v16, s[28:29] sc1
	global_load_dword v5, v16, s[30:31] sc1
	global_load_dword v6, v16, s[34:35] sc1
	global_load_dword v7, v16, s[36:37] sc1
	global_load_dword v8, v16, s[38:39] sc1
	global_load_dword v9, v16, s[40:41] sc1
	global_load_dword v10, v16, s[42:43] sc1
	global_load_dword v11, v16, s[44:45] sc1
	global_load_dword v12, v16, s[46:47] sc1
	global_load_dword v13, v16, s[48:49] sc1
	global_load_dword v14, v16, s[50:51] sc1
	s_mov_b64 s[52:53], -1
	s_mov_b64 s[54:55], -1
	s_waitcnt vmcnt(14)
	v_add_u32_e32 v17, v0, v15
	s_waitcnt vmcnt(13)
	v_add_u32_e32 v17, v17, v1
	s_waitcnt vmcnt(12)
	v_add_u32_e32 v17, v17, v2
	s_waitcnt vmcnt(11)
	v_add_u32_e32 v17, v17, v3
	s_waitcnt vmcnt(10)
	v_add_u32_e32 v17, v17, v4
	s_waitcnt vmcnt(9)
	v_add_u32_e32 v17, v17, v5
	s_waitcnt vmcnt(8)
	v_add_u32_e32 v17, v17, v6
	s_waitcnt vmcnt(7)
	v_add_u32_e32 v17, v17, v7
	s_waitcnt vmcnt(6)
	v_add_u32_e32 v17, v17, v8
	s_waitcnt vmcnt(5)
	v_add_u32_e32 v17, v17, v9
	s_waitcnt vmcnt(4)
	v_add_u32_e32 v17, v17, v10
	s_waitcnt vmcnt(3)
	v_add_u32_e32 v17, v17, v11
	s_waitcnt vmcnt(2)
	v_add_u32_e32 v17, v17, v12
	s_waitcnt vmcnt(1)
	v_add_u32_e32 v17, v17, v13
	s_waitcnt vmcnt(0)
	v_add_u32_e32 v17, v17, v14
	v_cmp_eq_u32_e32 vcc, s58, v17
	s_cbranch_vccnz .LBB0_1373
	s_and_b32 s52, s33, 0xff
	s_cmp_eq_u32 s52, 0
	s_mov_b64 s[52:53], -1
	s_mov_b64 s[56:57], -1
	s_cbranch_scc1 .LBB0_1378
	s_and_b64 vcc, exec, s[56:57]
	s_cbranch_vccz .LBB0_1373

; __device__ __forceinline__ unsigned xb_ld(unsigned* p)              { return __hip_atomic_load(p, __ATOMIC_RELAXED, __HIP_MEMORY_SCOPE_AGENT); }
; __device__ __forceinline__ unsigned xb_add(unsigned* p, unsigned v) { return __hip_atomic_fetch_add(p, v, __ATOMIC_RELAXED, __HIP_MEMORY_SCOPE_AGENT); }
; #define XB_SPIN(cond, bar) do { unsigned _sp = 0; while (cond) { __builtin_amdgcn_s_sleep(1); \
;     if ((++_sp & 255u) == 0u) { if (xb_ld(&(bar)[XB_TMO])) break; if (_sp > XB_SPIN_CAP) { atomicAdd(&(bar)[XB_TMO], 1u); break; } } } } while (0)
; __device__ __forceinline__ void xcd_barrier(const XcdBarrier& b) {
;     ...
;             else XB_SPIN(xb_ld(&bar[XB_TOPGEN]) == tg, bar);
;             __builtin_amdgcn_fence(__ATOMIC_ACQUIRE, "agent");
;             xb_add(&bar[XB_XGEN(b.x)], 1u);
;             asm volatile("s_waitcnt vmcnt(0)" ::: "memory");
;         } else {
;             XB_SPIN(xb_ld(&bar[XB_XGEN(b.x)]) == gen, bar);
.LBB0_1392:
	s_and_b32 s34, s33, 0xff
	s_mov_b64 s[30:31], -1
	s_cmp_lg_u32 s34, 0
	s_mov_b64 s[36:37], -1
	s_cbranch_scc0 .LBB0_1395
	s_and_b64 vcc, exec, s[36:37]
	s_cbranch_vccz .LBB0_1391

; __device__ __forceinline__ unsigned xb_ld(unsigned* p)              { return __hip_atomic_load(p, __ATOMIC_RELAXED, __HIP_MEMORY_SCOPE_AGENT); }
; __device__ __forceinline__ unsigned xb_add(unsigned* p, unsigned v) { return __hip_atomic_fetch_add(p, v, __ATOMIC_RELAXED, __HIP_MEMORY_SCOPE_AGENT); }
; #define XB_SPIN(cond, bar) do { unsigned _sp = 0; while (cond) { __builtin_amdgcn_s_sleep(1); \
;     if ((++_sp & 255u) == 0u) { if (xb_ld(&(bar)[XB_TMO])) break; if (_sp > XB_SPIN_CAP) { atomicAdd(&(bar)[XB_TMO], 1u); break; } } } } while (0)
; __device__ __forceinline__ void xcd_barrier(const XcdBarrier& b) {
;     ...
;             else XB_SPIN(xb_ld(&bar[XB_TOPGEN]) == tg, bar);
;             __builtin_amdgcn_fence(__ATOMIC_ACQUIRE, "agent");
;             xb_add(&bar[XB_XGEN(b.x)], 1u);
;             asm volatile("s_waitcnt vmcnt(0)" ::: "memory");
;         } else {
;             XB_SPIN(xb_ld(&bar[XB_XGEN(b.x)]) == gen, bar);
.LBB0_1409:
	s_and_b32 s30, s33, 0xff
	s_cmp_lg_u32 s30, 0
	s_mov_b64 s[34:35], -1
	s_cbranch_scc0 .LBB0_1412
	s_mov_b64 s[36:37], -1
	s_and_b64 vcc, exec, s[34:35]
	s_cbranch_vccz .LBB0_1408

; __device__ __forceinline__ unsigned xb_ld(unsigned* p)              { return __hip_atomic_load(p, __ATOMIC_RELAXED, __HIP_MEMORY_SCOPE_AGENT); }
; __device__ __forceinline__ void xcd_barrier_complete(unsigned* bar, unsigned x, unsigned& nloc, unsigned& nx) {
;     ...
;     for (;;) {
;         sum = 0u; cnt = 0u; mine = 0u;
; #pragma unroll
;         for (unsigned j = 0; j < 16; ++j) { const unsigned c = xb_ld(&bar[XB_XCNT(j)]); sum += c; cnt += (c > 0u) ? 1u : 0u; mine = (j == x) ? c : mine; }
;         if (sum == G) break;
;         __builtin_amdgcn_s_sleep(1);
;         if ((++sp & 255u) == 0u) { if (xb_ld(&bar[XB_TMO])) break; if (sp > XB_SPIN_CAP) { atomicAdd(&bar[XB_TMO], 1u); break; } }
;     }
.LBB0_1538:
	global_load_dword v15, v16, s[10:11] sc1
	global_load_dword v0, v16, s[12:13] sc1
	global_load_dword v1, v16, s[14:15] sc1
	global_load_dword v2, v16, s[16:17] sc1
	global_load_dword v3, v16, s[18:19] sc1
	global_load_dword v4, v16, s[26:27] sc1
	global_load_dword v5, v16, s[28:29] sc1
	global_load_dword v6, v16, s[30:31] sc1
	global_load_dword v7, v16, s[34:35] sc1
	global_load_dword v8, v16, s[36:37] sc1
	global_load_dword v9, v16, s[38:39] sc1
	global_load_dword v10, v16, s[40:41] sc1
	global_load_dword v11, v16, s[42:43] sc1
	global_load_dword v12, v16, s[44:45] sc1
	global_load_dword v13, v16, s[46:47] sc1
	global_load_dword v14, v16, s[48:49] sc1
	s_mov_b64 s[50:51], -1
	s_mov_b64 s[52:53], -1
	s_waitcnt vmcnt(14)
	v_add_u32_e32 v17, v0, v15
	s_waitcnt vmcnt(13)
	v_add_u32_e32 v17, v17, v1
	s_waitcnt vmcnt(12)
	v_add_u32_e32 v17, v17, v2
	s_waitcnt vmcnt(11)
	v_add_u32_e32 v17, v17, v3
	s_waitcnt vmcnt(10)
	v_add_u32_e32 v17, v17, v4
	s_waitcnt vmcnt(9)
	v_add_u32_e32 v17, v17, v5
	s_waitcnt vmcnt(8)
	v_add_u32_e32 v17, v17, v6
	s_waitcnt vmcnt(7)
	v_add_u32_e32 v17, v17, v7
	s_waitcnt vmcnt(6)
	v_add_u32_e32 v17, v17, v8
	s_waitcnt vmcnt(5)
	v_add_u32_e32 v17, v17, v9
	s_waitcnt vmcnt(4)
	v_add_u32_e32 v17, v17, v10
	s_waitcnt vmcnt(3)
	v_add_u32_e32 v17, v17, v11
	s_waitcnt vmcnt(2)
	v_add_u32_e32 v17, v17, v12
	s_waitcnt vmcnt(1)
	v_add_u32_e32 v17, v17, v13
	s_waitcnt vmcnt(0)
	v_add_u32_e32 v17, v17, v14
	v_cmp_eq_u32_e32 vcc, s21, v17
	s_cbranch_vccnz .LBB0_1537
	s_and_b32 s50, s33, 0xff
	s_cmp_eq_u32 s50, 0
	s_mov_b64 s[50:51], -1
	s_mov_b64 s[54:55], -1
	s_cbranch_scc1 .LBB0_1542
	s_and_b64 vcc, exec, s[54:55]
	s_cbranch_vccz .LBB0_1537

; __device__ __forceinline__ unsigned xb_ld(unsigned* p)              { return __hip_atomic_load(p, __ATOMIC_RELAXED, __HIP_MEMORY_SCOPE_AGENT); }
; __device__ __forceinline__ unsigned xb_add(unsigned* p, unsigned v) { return __hip_atomic_fetch_add(p, v, __ATOMIC_RELAXED, __HIP_MEMORY_SCOPE_AGENT); }
; #define XB_SPIN(cond, bar) do { unsigned _sp = 0; while (cond) { __builtin_amdgcn_s_sleep(1); \
;     if ((++_sp & 255u) == 0u) { if (xb_ld(&(bar)[XB_TMO])) break; if (_sp > XB_SPIN_CAP) { atomicAdd(&(bar)[XB_TMO], 1u); break; } } } } while (0)
; __device__ __forceinline__ void xcd_barrier(const XcdBarrier& b) {
;     ...
;             else XB_SPIN(xb_ld(&bar[XB_TOPGEN]) == tg, bar);
;             __builtin_amdgcn_fence(__ATOMIC_ACQUIRE, "agent");
;             xb_add(&bar[XB_XGEN(b.x)], 1u);
;             asm volatile("s_waitcnt vmcnt(0)" ::: "memory");
;         } else {
;             XB_SPIN(xb_ld(&bar[XB_XGEN(b.x)]) == gen, bar);
.LBB0_1556:
	s_and_b32 s21, s3, 0xff
	s_mov_b64 s[26:27], -1
	s_cmp_lg_u32 s21, 0
	s_mov_b64 s[30:31], -1
	s_cbranch_scc0 .LBB0_1559
	s_and_b64 vcc, exec, s[30:31]
	s_cbranch_vccz .LBB0_1555

; __device__ __forceinline__ unsigned xb_ld(unsigned* p)              { return __hip_atomic_load(p, __ATOMIC_RELAXED, __HIP_MEMORY_SCOPE_AGENT); }
; __device__ __forceinline__ unsigned xb_add(unsigned* p, unsigned v) { return __hip_atomic_fetch_add(p, v, __ATOMIC_RELAXED, __HIP_MEMORY_SCOPE_AGENT); }
; #define XB_SPIN(cond, bar) do { unsigned _sp = 0; while (cond) { __builtin_amdgcn_s_sleep(1); \
;     if ((++_sp & 255u) == 0u) { if (xb_ld(&(bar)[XB_TMO])) break; if (_sp > XB_SPIN_CAP) { atomicAdd(&(bar)[XB_TMO], 1u); break; } } } } while (0)
; __device__ __forceinline__ void xcd_barrier(const XcdBarrier& b) {
;     ...
;             else XB_SPIN(xb_ld(&bar[XB_TOPGEN]) == tg, bar);
;             __builtin_amdgcn_fence(__ATOMIC_ACQUIRE, "agent");
;             xb_add(&bar[XB_XGEN(b.x)], 1u);
;             asm volatile("s_waitcnt vmcnt(0)" ::: "memory");
;         } else {
;             XB_SPIN(xb_ld(&bar[XB_XGEN(b.x)]) == gen, bar);
.LBB0_1573:
	s_and_b32 s21, s3, 0xff
	s_cmp_lg_u32 s21, 0
	s_mov_b64 s[26:27], -1
	s_cbranch_scc0 .LBB0_1576
	s_mov_b64 s[28:29], -1
	s_and_b64 vcc, exec, s[26:27]
	s_cbranch_vccz .LBB0_1572
